# K=2 late barrier + grid barrier: non-leader L1 invalidate issued before the release spin instead of after it (nothing allocates in L1 while spinning)
# speedup vs baseline: 1.0322x; 1.0322x over previous
.LBB0_259:
	s_lshl_b32 s4, s97, 8
	s_add_u32 s4, s78, s4
	s_addc_u32 s5, s79, 0
	v_mov_b32_e32 v3, 0x1000
	v_mov_b32_e32 v5, 1
	global_atomic_add v5, v3, v5, s[4:5] offset:1024 sc0
	v_cvt_f32_u32_e32 v3, v4
	v_sub_u32_e32 v6, 0, v4
	v_rcp_iflag_f32_e32 v3, v3
	s_nop 0
	v_mul_f32_e32 v3, 0x4f7ffffe, v3
	v_cvt_u32_f32_e32 v3, v3
	v_mul_lo_u32 v6, v6, v3
	v_mul_hi_u32 v6, v3, v6
	v_add_u32_e32 v3, v3, v6
	s_waitcnt vmcnt(0)
	v_mul_hi_u32 v3, v5, v3
	v_mul_lo_u32 v6, v3, v4
	v_sub_u32_e32 v6, v5, v6
	v_add_u32_e32 v7, 1, v3
	v_cmp_ge_u32_e32 vcc, v6, v4
	v_add_u32_e32 v5, 1, v5
	s_nop 0
	v_cndmask_b32_e32 v3, v3, v7, vcc
	v_sub_u32_e32 v7, v6, v4
	v_cndmask_b32_e32 v6, v6, v7, vcc
	v_add_u32_e32 v7, 1, v3
	v_cmp_ge_u32_e32 vcc, v6, v4
	s_nop 1
	v_cndmask_b32_e32 v3, v3, v7, vcc
	v_mul_lo_u32 v6, v4, v3
	v_add_u32_e32 v4, v6, v4
	v_cmp_ne_u32_e32 vcc, v5, v4
	s_and_saveexec_b64 s[6:7], vcc
	s_xor_b64 s[6:7], exec, s[6:7]
	s_cbranch_execz .LBB0_273
	s_waitcnt lgkmcnt(0)
	buffer_inv sc1
	v_mov_b32_e32 v2, 0x2000
	global_load_dword v2, v2, s[4:5] offset:1024 sc1
	s_add_u32 s12, s4, 0x2400
	s_addc_u32 s13, s5, 0
	s_waitcnt vmcnt(0)
	v_cmp_eq_u32_e32 vcc, v2, v3
	s_and_saveexec_b64 s[10:11], vcc
	s_cbranch_execz .LBB0_272
	s_mov_b32 s30, 1
	s_mov_b64 s[16:17], 0
	v_mov_b32_e32 v2, 0
	s_branch .LBB0_263

.LBB0_272:
	s_or_b64 exec, exec, s[10:11]
	s_waitcnt vmcnt(0)
	s_waitcnt vmcnt(0)

.LBB0_354:
	s_lshl_b32 s4, s97, 8
	s_add_u32 s4, s78, s4
	s_addc_u32 s5, s79, 0
	v_mov_b32_e32 v3, 0x1000
	v_mov_b32_e32 v5, 1
	global_atomic_add v5, v3, v5, s[4:5] offset:1024 sc0
	v_cvt_f32_u32_e32 v3, v4
	v_sub_u32_e32 v6, 0, v4
	v_rcp_iflag_f32_e32 v3, v3
	s_nop 0
	v_mul_f32_e32 v3, 0x4f7ffffe, v3
	v_cvt_u32_f32_e32 v3, v3
	v_mul_lo_u32 v6, v6, v3
	v_mul_hi_u32 v6, v3, v6
	v_add_u32_e32 v3, v3, v6
	s_waitcnt vmcnt(0)
	v_mul_hi_u32 v3, v5, v3
	v_mul_lo_u32 v6, v3, v4
	v_sub_u32_e32 v6, v5, v6
	v_add_u32_e32 v7, 1, v3
	v_cmp_ge_u32_e32 vcc, v6, v4
	v_add_u32_e32 v5, 1, v5
	s_nop 0
	v_cndmask_b32_e32 v3, v3, v7, vcc
	v_sub_u32_e32 v7, v6, v4
	v_cndmask_b32_e32 v6, v6, v7, vcc
	v_add_u32_e32 v7, 1, v3
	v_cmp_ge_u32_e32 vcc, v6, v4
	s_nop 1
	v_cndmask_b32_e32 v3, v3, v7, vcc
	v_mul_lo_u32 v6, v4, v3
	v_add_u32_e32 v4, v6, v4
	v_cmp_ne_u32_e32 vcc, v5, v4
	s_and_saveexec_b64 s[6:7], vcc
	s_xor_b64 s[6:7], exec, s[6:7]
	s_cbranch_execz .LBB0_368
	s_waitcnt lgkmcnt(0)
	buffer_inv sc1
	v_mov_b32_e32 v2, 0x2000
	global_load_dword v2, v2, s[4:5] offset:1024 sc1
	s_add_u32 s10, s4, 0x2400
	s_addc_u32 s11, s5, 0
	s_waitcnt vmcnt(0)
	v_cmp_eq_u32_e32 vcc, v2, v3
	s_and_saveexec_b64 s[8:9], vcc
	s_cbranch_execz .LBB0_367
	s_mov_b32 s26, 1
	s_mov_b64 s[12:13], 0
	v_mov_b32_e32 v2, 0
	s_branch .LBB0_358

.LBB0_367:
	s_or_b64 exec, exec, s[8:9]
	s_waitcnt vmcnt(0)
	s_waitcnt vmcnt(0)

.LBB0_1411:
	s_lshl_b32 s4, s97, 8
	s_add_u32 s4, s78, s4
	s_addc_u32 s5, s79, 0
	v_mov_b32_e32 v3, 0x1000
	v_mov_b32_e32 v5, 1
	global_atomic_add v5, v3, v5, s[4:5] offset:1024 sc0
	v_cvt_f32_u32_e32 v3, v4
	v_sub_u32_e32 v6, 0, v4
	v_rcp_iflag_f32_e32 v3, v3
	s_nop 0
	v_mul_f32_e32 v3, 0x4f7ffffe, v3
	v_cvt_u32_f32_e32 v3, v3
	v_mul_lo_u32 v6, v6, v3
	v_mul_hi_u32 v6, v3, v6
	v_add_u32_e32 v3, v3, v6
	s_waitcnt vmcnt(0)
	v_mul_hi_u32 v3, v5, v3
	v_mul_lo_u32 v6, v3, v4
	v_sub_u32_e32 v6, v5, v6
	v_add_u32_e32 v7, 1, v3
	v_cmp_ge_u32_e32 vcc, v6, v4
	v_add_u32_e32 v5, 1, v5
	s_nop 0
	v_cndmask_b32_e32 v3, v3, v7, vcc
	v_sub_u32_e32 v7, v6, v4
	v_cndmask_b32_e32 v6, v6, v7, vcc
	v_add_u32_e32 v7, 1, v3
	v_cmp_ge_u32_e32 vcc, v6, v4
	s_nop 1
	v_cndmask_b32_e32 v3, v3, v7, vcc
	v_mul_lo_u32 v6, v4, v3
	v_add_u32_e32 v4, v6, v4
	v_cmp_ne_u32_e32 vcc, v5, v4
	s_and_saveexec_b64 s[6:7], vcc
	s_xor_b64 s[6:7], exec, s[6:7]
	s_cbranch_execz .LBB0_1425
	s_waitcnt lgkmcnt(0)
	buffer_inv sc1
	v_mov_b32_e32 v2, 0x2000
	global_load_dword v2, v2, s[4:5] offset:1024 sc1
	s_add_u32 s10, s4, 0x2400
	s_addc_u32 s11, s5, 0
	s_waitcnt vmcnt(0)
	v_cmp_eq_u32_e32 vcc, v2, v3
	s_and_saveexec_b64 s[8:9], vcc
	s_cbranch_execz .LBB0_1424
	s_mov_b32 s22, 1
	s_mov_b64 s[12:13], 0
	v_mov_b32_e32 v2, 0
	s_branch .LBB0_1415
